# ada phase: second round of items split 16 rows per workgroup across all 256 WGs instead of 32 WGs doing whole items
# baseline (speedup 1.0000x reference)
.LBB0_19:
	s_lshl_b32 s8, s8, 3
	v_lshl_add_u64 v[2:3], v[2:3], 2, s[28:29]
	v_mad_i64_i32 v[14:15], s[0:1], s8, v1, v[2:3]
	s_waitcnt vmcnt(0)
	v_add_f32_e32 v10, v10, v12
	s_or_b32 s0, s8, 1
	global_atomic_add_f32 v[14:15], v10, off
	v_mad_i64_i32 v[14:15], s[0:1], s0, v1, v[2:3]
	v_add_f32_e32 v10, v11, v12
	s_or_b32 s0, s8, 2
	global_atomic_add_f32 v[14:15], v10, off
	v_mad_i64_i32 v[10:11], s[0:1], s0, v1, v[2:3]
	v_add_f32_e32 v8, v8, v12
	s_or_b32 s0, s8, 3
	global_atomic_add_f32 v[10:11], v8, off
	v_mad_i64_i32 v[10:11], s[0:1], s0, v1, v[2:3]
	v_add_f32_e32 v8, v9, v12
	s_or_b32 s0, s8, 4
	global_atomic_add_f32 v[10:11], v8, off
	v_mad_i64_i32 v[8:9], s[0:1], s0, v1, v[2:3]
	v_add_f32_e32 v6, v6, v12
	s_or_b32 s0, s8, 5
	global_atomic_add_f32 v[8:9], v6, off
	v_mad_i64_i32 v[8:9], s[0:1], s0, v1, v[2:3]
	v_add_f32_e32 v6, v7, v12
	s_or_b32 s0, s8, 6
	global_atomic_add_f32 v[8:9], v6, off
	v_mad_i64_i32 v[6:7], s[0:1], s0, v1, v[2:3]
	v_add_f32_e32 v4, v4, v12
	s_or_b32 s0, s8, 7
	global_atomic_add_f32 v[6:7], v4, off
	v_mad_i64_i32 v[2:3], s[0:1], s0, v1, v[2:3]
	v_add_f32_e32 v4, v5, v12
	global_atomic_add_f32 v[2:3], v4, off
	s_cmpk_ge_i32 s7, 0x100
	s_cbranch_scc1 .LBB0_24
	s_lshr_b32 s7, s2, 3
	s_addk_i32 s7, 0x100
.LBB0_20:
	s_mul_hi_i32 s0, s7, 0x38e38e39
	s_lshr_b32 s1, s0, 31
	s_ashr_i32 s8, s0, 5
	s_add_i32 s8, s8, s1
	s_mul_i32 s0, s8, 0x90
	s_sub_i32 s0, s7, s0
	s_lshl_b32 s1, s0, 6
	v_mov_b32_e32 v2, v179
	s_and_b32 s9, s0, 7
	s_and_b32 s0, s7, 7
	s_and_b32 s1, s1, 0xfffffe00
	s_mul_i32 s14, s8, 0x2400000
	s_mul_i32 s0, s0, 0x480000
	v_add_u32_e32 v2, s1, v2
	s_mul_hi_i32 s1, s8, 0x2400000
	s_add_u32 s0, s14, s0
	v_readlane_b32 s36, v249, 0
	s_addc_u32 s1, s1, 0
	v_readlane_b32 s40, v249, 4
	v_readlane_b32 s41, v249, 5
	s_add_u32 s0, s40, s0
	v_ashrrev_i32_e32 v3, 31, v2
	s_addc_u32 s1, s41, s1
	v_lshl_add_u64 v[12:13], v[2:3], 2, s[0:1]
	s_lshl_b32 s0, s9, 9
	v_mov_b32_e32 v4, 0
	s_add_i32 s14, s0, 0
	s_mov_b64 s[0:1], 0
	v_mov_b32_e32 v5, v4
	v_mov_b32_e32 v10, v4
	v_mov_b32_e32 v11, v4
	v_mov_b32_e32 v8, v4
	v_mov_b32_e32 v9, v4
	v_mov_b32_e32 v6, v4
	v_mov_b32_e32 v7, v4
	v_readlane_b32 s37, v249, 1
	v_readlane_b32 s38, v249, 2
	v_readlane_b32 s39, v249, 3
	v_readlane_b32 s42, v249, 6
	v_readlane_b32 s43, v249, 7
	s_cmpk_lt_i32 s7, 0x100
	s_cbranch_scc1 .Lada_full
	s_and_b32 s0, s2, 7
	s_or_b32 s9, s9, s0
	s_lshl_b32 s1, s0, 6
	s_add_i32 s14, s14, s1
	s_mul_i32 s0, s0, 0x90000
	s_mov_b32 s1, 0
	v_lshl_add_u64 v[12:13], v[12:13], 0, s[0:1]
	v_mov_b32_e32 v202, s14
	v_mov_b32_e32 v194, v12
	v_mov_b32_e32 v195, v13
	v_add_co_u32_e32 v196, vcc, s4, v12
	s_nop 1
	v_addc_co_u32_e32 v197, vcc, 0, v13, vcc
	v_add_co_u32_e32 v198, vcc, s5, v12
	s_nop 1
	v_addc_co_u32_e32 v199, vcc, 0, v13, vcc
	v_add_co_u32_e32 v200, vcc, s6, v12
	s_nop 1
	v_addc_co_u32_e32 v201, vcc, 0, v13, vcc
	s_mov_b32 s0, 0x24000
	s_mov_b32 s1, 0
	global_load_dword v64, v[194:195], off
	v_lshl_add_u64 v[194:195], v[194:195], 0, s[0:1]
	global_load_dword v65, v[196:197], off
	v_lshl_add_u64 v[196:197], v[196:197], 0, s[0:1]
	global_load_dword v66, v[198:199], off
	v_lshl_add_u64 v[198:199], v[198:199], 0, s[0:1]
	global_load_dword v67, v[200:201], off
	v_lshl_add_u64 v[200:201], v[200:201], 0, s[0:1]
	global_load_dword v68, v[194:195], off
	v_lshl_add_u64 v[194:195], v[194:195], 0, s[0:1]
	global_load_dword v69, v[196:197], off
	v_lshl_add_u64 v[196:197], v[196:197], 0, s[0:1]
	global_load_dword v70, v[198:199], off
	v_lshl_add_u64 v[198:199], v[198:199], 0, s[0:1]
	global_load_dword v71, v[200:201], off
	v_lshl_add_u64 v[200:201], v[200:201], 0, s[0:1]
	global_load_dword v72, v[194:195], off
	v_lshl_add_u64 v[194:195], v[194:195], 0, s[0:1]
	global_load_dword v73, v[196:197], off
	v_lshl_add_u64 v[196:197], v[196:197], 0, s[0:1]
	global_load_dword v74, v[198:199], off
	v_lshl_add_u64 v[198:199], v[198:199], 0, s[0:1]
	global_load_dword v75, v[200:201], off
	v_lshl_add_u64 v[200:201], v[200:201], 0, s[0:1]
	global_load_dword v76, v[194:195], off
	global_load_dword v77, v[196:197], off
	global_load_dword v78, v[198:199], off
	global_load_dword v79, v[200:201], off
	ds_read_b128 v[14:17], v202 offset:0
	ds_read_b128 v[18:21], v202 offset:4096
	ds_read_b128 v[22:25], v202 offset:8192
	ds_read_b128 v[26:29], v202 offset:12288
	ds_read_b128 v[30:33], v202 offset:16384
	ds_read_b128 v[34:37], v202 offset:20480
	ds_read_b128 v[38:41], v202 offset:24576
	ds_read_b128 v[42:45], v202 offset:28672
	ds_read_b128 v[204:207], v202 offset:16
	ds_read_b128 v[208:211], v202 offset:4112
	ds_read_b128 v[212:215], v202 offset:8208
	ds_read_b128 v[216:219], v202 offset:12304
	ds_read_b128 v[220:223], v202 offset:16400
	ds_read_b128 v[224:227], v202 offset:20496
	ds_read_b128 v[228:231], v202 offset:24592
	ds_read_b128 v[232:235], v202 offset:28688
	s_waitcnt vmcnt(12) lgkmcnt(8)
	v_fma_f32 v10, v64, v14, v10
	v_fma_f32 v11, v64, v18, v11
	v_fma_f32 v8, v64, v22, v8
	v_fma_f32 v9, v64, v26, v9
	v_fma_f32 v6, v64, v30, v6
	v_fma_f32 v7, v64, v34, v7
	v_fma_f32 v4, v64, v38, v4
	v_fma_f32 v5, v64, v42, v5
	v_fma_f32 v10, v65, v15, v10
	v_fma_f32 v11, v65, v19, v11
	v_fma_f32 v8, v65, v23, v8
	v_fma_f32 v9, v65, v27, v9
	v_fma_f32 v6, v65, v31, v6
	v_fma_f32 v7, v65, v35, v7
	v_fma_f32 v4, v65, v39, v4
	v_fma_f32 v5, v65, v43, v5
	v_fma_f32 v10, v66, v16, v10
	v_fma_f32 v11, v66, v20, v11
	v_fma_f32 v8, v66, v24, v8
	v_fma_f32 v9, v66, v28, v9
	v_fma_f32 v6, v66, v32, v6
	v_fma_f32 v7, v66, v36, v7
	v_fma_f32 v4, v66, v40, v4
	v_fma_f32 v5, v66, v44, v5
	v_fma_f32 v10, v67, v17, v10
	v_fma_f32 v11, v67, v21, v11
	v_fma_f32 v8, v67, v25, v8
	v_fma_f32 v9, v67, v29, v9
	v_fma_f32 v6, v67, v33, v6
	v_fma_f32 v7, v67, v37, v7
	v_fma_f32 v4, v67, v41, v4
	v_fma_f32 v5, v67, v45, v5
	ds_read_b128 v[14:17], v202 offset:32
	ds_read_b128 v[18:21], v202 offset:4128
	ds_read_b128 v[22:25], v202 offset:8224
	ds_read_b128 v[26:29], v202 offset:12320
	ds_read_b128 v[30:33], v202 offset:16416
	ds_read_b128 v[34:37], v202 offset:20512
	ds_read_b128 v[38:41], v202 offset:24608
	ds_read_b128 v[42:45], v202 offset:28704
	s_waitcnt vmcnt(8) lgkmcnt(8)
	v_fma_f32 v10, v68, v204, v10
	v_fma_f32 v11, v68, v208, v11
	v_fma_f32 v8, v68, v212, v8
	v_fma_f32 v9, v68, v216, v9
	v_fma_f32 v6, v68, v220, v6
	v_fma_f32 v7, v68, v224, v7
	v_fma_f32 v4, v68, v228, v4
	v_fma_f32 v5, v68, v232, v5
	v_fma_f32 v10, v69, v205, v10
	v_fma_f32 v11, v69, v209, v11
	v_fma_f32 v8, v69, v213, v8
	v_fma_f32 v9, v69, v217, v9
	v_fma_f32 v6, v69, v221, v6
	v_fma_f32 v7, v69, v225, v7
	v_fma_f32 v4, v69, v229, v4
	v_fma_f32 v5, v69, v233, v5
	v_fma_f32 v10, v70, v206, v10
	v_fma_f32 v11, v70, v210, v11
	v_fma_f32 v8, v70, v214, v8
	v_fma_f32 v9, v70, v218, v9
	v_fma_f32 v6, v70, v222, v6
	v_fma_f32 v7, v70, v226, v7
	v_fma_f32 v4, v70, v230, v4
	v_fma_f32 v5, v70, v234, v5
	v_fma_f32 v10, v71, v207, v10
	v_fma_f32 v11, v71, v211, v11
	v_fma_f32 v8, v71, v215, v8
	v_fma_f32 v9, v71, v219, v9
	v_fma_f32 v6, v71, v223, v6
	v_fma_f32 v7, v71, v227, v7
	v_fma_f32 v4, v71, v231, v4
	v_fma_f32 v5, v71, v235, v5
	ds_read_b128 v[204:207], v202 offset:48
	ds_read_b128 v[208:211], v202 offset:4144
	ds_read_b128 v[212:215], v202 offset:8240
	ds_read_b128 v[216:219], v202 offset:12336
	ds_read_b128 v[220:223], v202 offset:16432
	ds_read_b128 v[224:227], v202 offset:20528
	ds_read_b128 v[228:231], v202 offset:24624
	ds_read_b128 v[232:235], v202 offset:28720
	s_waitcnt vmcnt(4) lgkmcnt(8)
	v_fma_f32 v10, v72, v14, v10
	v_fma_f32 v11, v72, v18, v11
	v_fma_f32 v8, v72, v22, v8
	v_fma_f32 v9, v72, v26, v9
	v_fma_f32 v6, v72, v30, v6
	v_fma_f32 v7, v72, v34, v7
	v_fma_f32 v4, v72, v38, v4
	v_fma_f32 v5, v72, v42, v5
	v_fma_f32 v10, v73, v15, v10
	v_fma_f32 v11, v73, v19, v11
	v_fma_f32 v8, v73, v23, v8
	v_fma_f32 v9, v73, v27, v9
	v_fma_f32 v6, v73, v31, v6
	v_fma_f32 v7, v73, v35, v7
	v_fma_f32 v4, v73, v39, v4
	v_fma_f32 v5, v73, v43, v5
	v_fma_f32 v10, v74, v16, v10
	v_fma_f32 v11, v74, v20, v11
	v_fma_f32 v8, v74, v24, v8
	v_fma_f32 v9, v74, v28, v9
	v_fma_f32 v6, v74, v32, v6
	v_fma_f32 v7, v74, v36, v7
	v_fma_f32 v4, v74, v40, v4
	v_fma_f32 v5, v74, v44, v5
	v_fma_f32 v10, v75, v17, v10
	v_fma_f32 v11, v75, v21, v11
	v_fma_f32 v8, v75, v25, v8
	v_fma_f32 v9, v75, v29, v9
	v_fma_f32 v6, v75, v33, v6
	v_fma_f32 v7, v75, v37, v7
	v_fma_f32 v4, v75, v41, v4
	v_fma_f32 v5, v75, v45, v5
	s_waitcnt vmcnt(0) lgkmcnt(0)
	v_fma_f32 v10, v76, v204, v10
	v_fma_f32 v11, v76, v208, v11
	v_fma_f32 v8, v76, v212, v8
	v_fma_f32 v9, v76, v216, v9
	v_fma_f32 v6, v76, v220, v6
	v_fma_f32 v7, v76, v224, v7
	v_fma_f32 v4, v76, v228, v4
	v_fma_f32 v5, v76, v232, v5
	v_fma_f32 v10, v77, v205, v10
	v_fma_f32 v11, v77, v209, v11
	v_fma_f32 v8, v77, v213, v8
	v_fma_f32 v9, v77, v217, v9
	v_fma_f32 v6, v77, v221, v6
	v_fma_f32 v7, v77, v225, v7
	v_fma_f32 v4, v77, v229, v4
	v_fma_f32 v5, v77, v233, v5
	v_fma_f32 v10, v78, v206, v10
	v_fma_f32 v11, v78, v210, v11
	v_fma_f32 v8, v78, v214, v8
	v_fma_f32 v9, v78, v218, v9
	v_fma_f32 v6, v78, v222, v6
	v_fma_f32 v7, v78, v226, v7
	v_fma_f32 v4, v78, v230, v4
	v_fma_f32 v5, v78, v234, v5
	v_fma_f32 v10, v79, v207, v10
	v_fma_f32 v11, v79, v211, v11
	v_fma_f32 v8, v79, v215, v8
	v_fma_f32 v9, v79, v219, v9
	v_fma_f32 v6, v79, v223, v6
	v_fma_f32 v7, v79, v227, v7
	v_fma_f32 v4, v79, v231, v4
	v_fma_f32 v5, v79, v235, v5
	s_branch .Lada_join
.Lada_full:
	v_mov_b32_e32 v202, s14
	v_mov_b32_e32 v194, v12
	v_mov_b32_e32 v195, v13
	v_add_co_u32_e32 v196, vcc, s4, v12
	s_nop 1
	v_addc_co_u32_e32 v197, vcc, 0, v13, vcc
	v_add_co_u32_e32 v198, vcc, s5, v12
	s_nop 1
	v_addc_co_u32_e32 v199, vcc, 0, v13, vcc
	v_add_co_u32_e32 v200, vcc, s6, v12
	s_nop 1
	v_addc_co_u32_e32 v201, vcc, 0, v13, vcc
	s_mov_b32 s0, 0x24000
	s_mov_b32 s1, 0
	global_load_dword v64, v[194:195], off
	v_lshl_add_u64 v[194:195], v[194:195], 0, s[0:1]
	global_load_dword v65, v[196:197], off
	v_lshl_add_u64 v[196:197], v[196:197], 0, s[0:1]
	global_load_dword v66, v[198:199], off
	v_lshl_add_u64 v[198:199], v[198:199], 0, s[0:1]
	global_load_dword v67, v[200:201], off
	v_lshl_add_u64 v[200:201], v[200:201], 0, s[0:1]
	global_load_dword v68, v[194:195], off
	v_lshl_add_u64 v[194:195], v[194:195], 0, s[0:1]
	global_load_dword v69, v[196:197], off
	v_lshl_add_u64 v[196:197], v[196:197], 0, s[0:1]
	global_load_dword v70, v[198:199], off
	v_lshl_add_u64 v[198:199], v[198:199], 0, s[0:1]
	global_load_dword v71, v[200:201], off
	v_lshl_add_u64 v[200:201], v[200:201], 0, s[0:1]
	global_load_dword v72, v[194:195], off
	v_lshl_add_u64 v[194:195], v[194:195], 0, s[0:1]
	global_load_dword v73, v[196:197], off
	v_lshl_add_u64 v[196:197], v[196:197], 0, s[0:1]
	global_load_dword v74, v[198:199], off
	v_lshl_add_u64 v[198:199], v[198:199], 0, s[0:1]
	global_load_dword v75, v[200:201], off
	v_lshl_add_u64 v[200:201], v[200:201], 0, s[0:1]
	global_load_dword v76, v[194:195], off
	v_lshl_add_u64 v[194:195], v[194:195], 0, s[0:1]
	global_load_dword v77, v[196:197], off
	v_lshl_add_u64 v[196:197], v[196:197], 0, s[0:1]
	global_load_dword v78, v[198:199], off
	v_lshl_add_u64 v[198:199], v[198:199], 0, s[0:1]
	global_load_dword v79, v[200:201], off
	v_lshl_add_u64 v[200:201], v[200:201], 0, s[0:1]
	global_load_dword v80, v[194:195], off
	v_lshl_add_u64 v[194:195], v[194:195], 0, s[0:1]
	global_load_dword v81, v[196:197], off
	v_lshl_add_u64 v[196:197], v[196:197], 0, s[0:1]
	global_load_dword v82, v[198:199], off
	v_lshl_add_u64 v[198:199], v[198:199], 0, s[0:1]
	global_load_dword v83, v[200:201], off
	v_lshl_add_u64 v[200:201], v[200:201], 0, s[0:1]
	global_load_dword v84, v[194:195], off
	v_lshl_add_u64 v[194:195], v[194:195], 0, s[0:1]
	global_load_dword v85, v[196:197], off
	v_lshl_add_u64 v[196:197], v[196:197], 0, s[0:1]
	global_load_dword v86, v[198:199], off
	v_lshl_add_u64 v[198:199], v[198:199], 0, s[0:1]
	global_load_dword v87, v[200:201], off
	v_lshl_add_u64 v[200:201], v[200:201], 0, s[0:1]
	global_load_dword v88, v[194:195], off
	v_lshl_add_u64 v[194:195], v[194:195], 0, s[0:1]
	global_load_dword v89, v[196:197], off
	v_lshl_add_u64 v[196:197], v[196:197], 0, s[0:1]
	global_load_dword v90, v[198:199], off
	v_lshl_add_u64 v[198:199], v[198:199], 0, s[0:1]
	global_load_dword v91, v[200:201], off
	v_lshl_add_u64 v[200:201], v[200:201], 0, s[0:1]
	global_load_dword v92, v[194:195], off
	v_lshl_add_u64 v[194:195], v[194:195], 0, s[0:1]
	global_load_dword v93, v[196:197], off
	v_lshl_add_u64 v[196:197], v[196:197], 0, s[0:1]
	global_load_dword v94, v[198:199], off
	v_lshl_add_u64 v[198:199], v[198:199], 0, s[0:1]
	global_load_dword v95, v[200:201], off
	v_lshl_add_u64 v[200:201], v[200:201], 0, s[0:1]
	global_load_dword v96, v[194:195], off
	v_lshl_add_u64 v[194:195], v[194:195], 0, s[0:1]
	global_load_dword v97, v[196:197], off
	v_lshl_add_u64 v[196:197], v[196:197], 0, s[0:1]
	global_load_dword v98, v[198:199], off
	v_lshl_add_u64 v[198:199], v[198:199], 0, s[0:1]
	global_load_dword v99, v[200:201], off
	v_lshl_add_u64 v[200:201], v[200:201], 0, s[0:1]
	global_load_dword v100, v[194:195], off
	v_lshl_add_u64 v[194:195], v[194:195], 0, s[0:1]
	global_load_dword v101, v[196:197], off
	v_lshl_add_u64 v[196:197], v[196:197], 0, s[0:1]
	global_load_dword v102, v[198:199], off
	v_lshl_add_u64 v[198:199], v[198:199], 0, s[0:1]
	global_load_dword v103, v[200:201], off
	v_lshl_add_u64 v[200:201], v[200:201], 0, s[0:1]
	global_load_dword v104, v[194:195], off
	v_lshl_add_u64 v[194:195], v[194:195], 0, s[0:1]
	global_load_dword v105, v[196:197], off
	v_lshl_add_u64 v[196:197], v[196:197], 0, s[0:1]
	global_load_dword v106, v[198:199], off
	v_lshl_add_u64 v[198:199], v[198:199], 0, s[0:1]
	global_load_dword v107, v[200:201], off
	v_lshl_add_u64 v[200:201], v[200:201], 0, s[0:1]
	global_load_dword v108, v[194:195], off
	v_lshl_add_u64 v[194:195], v[194:195], 0, s[0:1]
	global_load_dword v109, v[196:197], off
	v_lshl_add_u64 v[196:197], v[196:197], 0, s[0:1]
	global_load_dword v110, v[198:199], off
	v_lshl_add_u64 v[198:199], v[198:199], 0, s[0:1]
	global_load_dword v111, v[200:201], off
	v_lshl_add_u64 v[200:201], v[200:201], 0, s[0:1]
	global_load_dword v112, v[194:195], off
	v_lshl_add_u64 v[194:195], v[194:195], 0, s[0:1]
	global_load_dword v113, v[196:197], off
	v_lshl_add_u64 v[196:197], v[196:197], 0, s[0:1]
	global_load_dword v114, v[198:199], off
	v_lshl_add_u64 v[198:199], v[198:199], 0, s[0:1]
	global_load_dword v115, v[200:201], off
	v_lshl_add_u64 v[200:201], v[200:201], 0, s[0:1]
	ds_read_b128 v[14:17], v202 offset:0
	ds_read_b128 v[18:21], v202 offset:4096
	ds_read_b128 v[22:25], v202 offset:8192
	ds_read_b128 v[26:29], v202 offset:12288
	ds_read_b128 v[30:33], v202 offset:16384
	ds_read_b128 v[34:37], v202 offset:20480
	ds_read_b128 v[38:41], v202 offset:24576
	ds_read_b128 v[42:45], v202 offset:28672
	ds_read_b128 v[204:207], v202 offset:16
	ds_read_b128 v[208:211], v202 offset:4112
	ds_read_b128 v[212:215], v202 offset:8208
	ds_read_b128 v[216:219], v202 offset:12304
	ds_read_b128 v[220:223], v202 offset:16400
	ds_read_b128 v[224:227], v202 offset:20496
	ds_read_b128 v[228:231], v202 offset:24592
	ds_read_b128 v[232:235], v202 offset:28688
	s_waitcnt vmcnt(48) lgkmcnt(8)
	v_fma_f32 v10, v64, v14, v10
	v_fma_f32 v11, v64, v18, v11
	v_fma_f32 v8, v64, v22, v8
	v_fma_f32 v9, v64, v26, v9
	v_fma_f32 v6, v64, v30, v6
	v_fma_f32 v7, v64, v34, v7
	v_fma_f32 v4, v64, v38, v4
	v_fma_f32 v5, v64, v42, v5
	v_fma_f32 v10, v65, v15, v10
	v_fma_f32 v11, v65, v19, v11
	v_fma_f32 v8, v65, v23, v8
	v_fma_f32 v9, v65, v27, v9
	v_fma_f32 v6, v65, v31, v6
	v_fma_f32 v7, v65, v35, v7
	v_fma_f32 v4, v65, v39, v4
	v_fma_f32 v5, v65, v43, v5
	v_fma_f32 v10, v66, v16, v10
	v_fma_f32 v11, v66, v20, v11
	v_fma_f32 v8, v66, v24, v8
	v_fma_f32 v9, v66, v28, v9
	v_fma_f32 v6, v66, v32, v6
	v_fma_f32 v7, v66, v36, v7
	v_fma_f32 v4, v66, v40, v4
	v_fma_f32 v5, v66, v44, v5
	v_fma_f32 v10, v67, v17, v10
	v_fma_f32 v11, v67, v21, v11
	v_fma_f32 v8, v67, v25, v8
	v_fma_f32 v9, v67, v29, v9
	v_fma_f32 v6, v67, v33, v6
	v_fma_f32 v7, v67, v37, v7
	v_fma_f32 v4, v67, v41, v4
	v_fma_f32 v5, v67, v45, v5
	global_load_dword v116, v[194:195], off
	v_lshl_add_u64 v[194:195], v[194:195], 0, s[0:1]
	global_load_dword v117, v[196:197], off
	v_lshl_add_u64 v[196:197], v[196:197], 0, s[0:1]
	global_load_dword v118, v[198:199], off
	v_lshl_add_u64 v[198:199], v[198:199], 0, s[0:1]
	global_load_dword v119, v[200:201], off
	v_lshl_add_u64 v[200:201], v[200:201], 0, s[0:1]
	ds_read_b128 v[14:17], v202 offset:32
	ds_read_b128 v[18:21], v202 offset:4128
	ds_read_b128 v[22:25], v202 offset:8224
	ds_read_b128 v[26:29], v202 offset:12320
	ds_read_b128 v[30:33], v202 offset:16416
	ds_read_b128 v[34:37], v202 offset:20512
	ds_read_b128 v[38:41], v202 offset:24608
	ds_read_b128 v[42:45], v202 offset:28704
	s_waitcnt vmcnt(48) lgkmcnt(8)
	v_fma_f32 v10, v68, v204, v10
	v_fma_f32 v11, v68, v208, v11
	v_fma_f32 v8, v68, v212, v8
	v_fma_f32 v9, v68, v216, v9
	v_fma_f32 v6, v68, v220, v6
	v_fma_f32 v7, v68, v224, v7
	v_fma_f32 v4, v68, v228, v4
	v_fma_f32 v5, v68, v232, v5
	v_fma_f32 v10, v69, v205, v10
	v_fma_f32 v11, v69, v209, v11
	v_fma_f32 v8, v69, v213, v8
	v_fma_f32 v9, v69, v217, v9
	v_fma_f32 v6, v69, v221, v6
	v_fma_f32 v7, v69, v225, v7
	v_fma_f32 v4, v69, v229, v4
	v_fma_f32 v5, v69, v233, v5
	v_fma_f32 v10, v70, v206, v10
	v_fma_f32 v11, v70, v210, v11
	v_fma_f32 v8, v70, v214, v8
	v_fma_f32 v9, v70, v218, v9
	v_fma_f32 v6, v70, v222, v6
	v_fma_f32 v7, v70, v226, v7
	v_fma_f32 v4, v70, v230, v4
	v_fma_f32 v5, v70, v234, v5
	v_fma_f32 v10, v71, v207, v10
	v_fma_f32 v11, v71, v211, v11
	v_fma_f32 v8, v71, v215, v8
	v_fma_f32 v9, v71, v219, v9
	v_fma_f32 v6, v71, v223, v6
	v_fma_f32 v7, v71, v227, v7
	v_fma_f32 v4, v71, v231, v4
	v_fma_f32 v5, v71, v235, v5
	global_load_dword v120, v[194:195], off
	v_lshl_add_u64 v[194:195], v[194:195], 0, s[0:1]
	global_load_dword v121, v[196:197], off
	v_lshl_add_u64 v[196:197], v[196:197], 0, s[0:1]
	global_load_dword v122, v[198:199], off
	v_lshl_add_u64 v[198:199], v[198:199], 0, s[0:1]
	global_load_dword v123, v[200:201], off
	v_lshl_add_u64 v[200:201], v[200:201], 0, s[0:1]
	ds_read_b128 v[204:207], v202 offset:48
	ds_read_b128 v[208:211], v202 offset:4144
	ds_read_b128 v[212:215], v202 offset:8240
	ds_read_b128 v[216:219], v202 offset:12336
	ds_read_b128 v[220:223], v202 offset:16432
	ds_read_b128 v[224:227], v202 offset:20528
	ds_read_b128 v[228:231], v202 offset:24624
	ds_read_b128 v[232:235], v202 offset:28720
	s_waitcnt vmcnt(48) lgkmcnt(8)
	v_fma_f32 v10, v72, v14, v10
	v_fma_f32 v11, v72, v18, v11
	v_fma_f32 v8, v72, v22, v8
	v_fma_f32 v9, v72, v26, v9
	v_fma_f32 v6, v72, v30, v6
	v_fma_f32 v7, v72, v34, v7
	v_fma_f32 v4, v72, v38, v4
	v_fma_f32 v5, v72, v42, v5
	v_fma_f32 v10, v73, v15, v10
	v_fma_f32 v11, v73, v19, v11
	v_fma_f32 v8, v73, v23, v8
	v_fma_f32 v9, v73, v27, v9
	v_fma_f32 v6, v73, v31, v6
	v_fma_f32 v7, v73, v35, v7
	v_fma_f32 v4, v73, v39, v4
	v_fma_f32 v5, v73, v43, v5
	v_fma_f32 v10, v74, v16, v10
	v_fma_f32 v11, v74, v20, v11
	v_fma_f32 v8, v74, v24, v8
	v_fma_f32 v9, v74, v28, v9
	v_fma_f32 v6, v74, v32, v6
	v_fma_f32 v7, v74, v36, v7
	v_fma_f32 v4, v74, v40, v4
	v_fma_f32 v5, v74, v44, v5
	v_fma_f32 v10, v75, v17, v10
	v_fma_f32 v11, v75, v21, v11
	v_fma_f32 v8, v75, v25, v8
	v_fma_f32 v9, v75, v29, v9
	v_fma_f32 v6, v75, v33, v6
	v_fma_f32 v7, v75, v37, v7
	v_fma_f32 v4, v75, v41, v4
	v_fma_f32 v5, v75, v45, v5
	global_load_dword v124, v[194:195], off
	v_lshl_add_u64 v[194:195], v[194:195], 0, s[0:1]
	global_load_dword v125, v[196:197], off
	v_lshl_add_u64 v[196:197], v[196:197], 0, s[0:1]
	global_load_dword v126, v[198:199], off
	v_lshl_add_u64 v[198:199], v[198:199], 0, s[0:1]
	global_load_dword v127, v[200:201], off
	v_lshl_add_u64 v[200:201], v[200:201], 0, s[0:1]
	ds_read_b128 v[14:17], v202 offset:64
	ds_read_b128 v[18:21], v202 offset:4160
	ds_read_b128 v[22:25], v202 offset:8256
	ds_read_b128 v[26:29], v202 offset:12352
	ds_read_b128 v[30:33], v202 offset:16448
	ds_read_b128 v[34:37], v202 offset:20544
	ds_read_b128 v[38:41], v202 offset:24640
	ds_read_b128 v[42:45], v202 offset:28736
	s_waitcnt vmcnt(48) lgkmcnt(8)
	v_fma_f32 v10, v76, v204, v10
	v_fma_f32 v11, v76, v208, v11
	v_fma_f32 v8, v76, v212, v8
	v_fma_f32 v9, v76, v216, v9
	v_fma_f32 v6, v76, v220, v6
	v_fma_f32 v7, v76, v224, v7
	v_fma_f32 v4, v76, v228, v4
	v_fma_f32 v5, v76, v232, v5
	v_fma_f32 v10, v77, v205, v10
	v_fma_f32 v11, v77, v209, v11
	v_fma_f32 v8, v77, v213, v8
	v_fma_f32 v9, v77, v217, v9
	v_fma_f32 v6, v77, v221, v6
	v_fma_f32 v7, v77, v225, v7
	v_fma_f32 v4, v77, v229, v4
	v_fma_f32 v5, v77, v233, v5
	v_fma_f32 v10, v78, v206, v10
	v_fma_f32 v11, v78, v210, v11
	v_fma_f32 v8, v78, v214, v8
	v_fma_f32 v9, v78, v218, v9
	v_fma_f32 v6, v78, v222, v6
	v_fma_f32 v7, v78, v226, v7
	v_fma_f32 v4, v78, v230, v4
	v_fma_f32 v5, v78, v234, v5
	v_fma_f32 v10, v79, v207, v10
	v_fma_f32 v11, v79, v211, v11
	v_fma_f32 v8, v79, v215, v8
	v_fma_f32 v9, v79, v219, v9
	v_fma_f32 v6, v79, v223, v6
	v_fma_f32 v7, v79, v227, v7
	v_fma_f32 v4, v79, v231, v4
	v_fma_f32 v5, v79, v235, v5
	global_load_dword v128, v[194:195], off
	v_lshl_add_u64 v[194:195], v[194:195], 0, s[0:1]
	global_load_dword v129, v[196:197], off
	v_lshl_add_u64 v[196:197], v[196:197], 0, s[0:1]
	global_load_dword v130, v[198:199], off
	v_lshl_add_u64 v[198:199], v[198:199], 0, s[0:1]
	global_load_dword v131, v[200:201], off
	v_lshl_add_u64 v[200:201], v[200:201], 0, s[0:1]
	ds_read_b128 v[204:207], v202 offset:80
	ds_read_b128 v[208:211], v202 offset:4176
	ds_read_b128 v[212:215], v202 offset:8272
	ds_read_b128 v[216:219], v202 offset:12368
	ds_read_b128 v[220:223], v202 offset:16464
	ds_read_b128 v[224:227], v202 offset:20560
	ds_read_b128 v[228:231], v202 offset:24656
	ds_read_b128 v[232:235], v202 offset:28752
	s_waitcnt vmcnt(48) lgkmcnt(8)
	v_fma_f32 v10, v80, v14, v10
	v_fma_f32 v11, v80, v18, v11
	v_fma_f32 v8, v80, v22, v8
	v_fma_f32 v9, v80, v26, v9
	v_fma_f32 v6, v80, v30, v6
	v_fma_f32 v7, v80, v34, v7
	v_fma_f32 v4, v80, v38, v4
	v_fma_f32 v5, v80, v42, v5
	v_fma_f32 v10, v81, v15, v10
	v_fma_f32 v11, v81, v19, v11
	v_fma_f32 v8, v81, v23, v8
	v_fma_f32 v9, v81, v27, v9
	v_fma_f32 v6, v81, v31, v6
	v_fma_f32 v7, v81, v35, v7
	v_fma_f32 v4, v81, v39, v4
	v_fma_f32 v5, v81, v43, v5
	v_fma_f32 v10, v82, v16, v10
	v_fma_f32 v11, v82, v20, v11
	v_fma_f32 v8, v82, v24, v8
	v_fma_f32 v9, v82, v28, v9
	v_fma_f32 v6, v82, v32, v6
	v_fma_f32 v7, v82, v36, v7
	v_fma_f32 v4, v82, v40, v4
	v_fma_f32 v5, v82, v44, v5
	v_fma_f32 v10, v83, v17, v10
	v_fma_f32 v11, v83, v21, v11
	v_fma_f32 v8, v83, v25, v8
	v_fma_f32 v9, v83, v29, v9
	v_fma_f32 v6, v83, v33, v6
	v_fma_f32 v7, v83, v37, v7
	v_fma_f32 v4, v83, v41, v4
	v_fma_f32 v5, v83, v45, v5
	global_load_dword v132, v[194:195], off
	v_lshl_add_u64 v[194:195], v[194:195], 0, s[0:1]
	global_load_dword v133, v[196:197], off
	v_lshl_add_u64 v[196:197], v[196:197], 0, s[0:1]
	global_load_dword v134, v[198:199], off
	v_lshl_add_u64 v[198:199], v[198:199], 0, s[0:1]
	global_load_dword v135, v[200:201], off
	v_lshl_add_u64 v[200:201], v[200:201], 0, s[0:1]
	ds_read_b128 v[14:17], v202 offset:96
	ds_read_b128 v[18:21], v202 offset:4192
	ds_read_b128 v[22:25], v202 offset:8288
	ds_read_b128 v[26:29], v202 offset:12384
	ds_read_b128 v[30:33], v202 offset:16480
	ds_read_b128 v[34:37], v202 offset:20576
	ds_read_b128 v[38:41], v202 offset:24672
	ds_read_b128 v[42:45], v202 offset:28768
	s_waitcnt vmcnt(48) lgkmcnt(8)
	v_fma_f32 v10, v84, v204, v10
	v_fma_f32 v11, v84, v208, v11
	v_fma_f32 v8, v84, v212, v8
	v_fma_f32 v9, v84, v216, v9
	v_fma_f32 v6, v84, v220, v6
	v_fma_f32 v7, v84, v224, v7
	v_fma_f32 v4, v84, v228, v4
	v_fma_f32 v5, v84, v232, v5
	v_fma_f32 v10, v85, v205, v10
	v_fma_f32 v11, v85, v209, v11
	v_fma_f32 v8, v85, v213, v8
	v_fma_f32 v9, v85, v217, v9
	v_fma_f32 v6, v85, v221, v6
	v_fma_f32 v7, v85, v225, v7
	v_fma_f32 v4, v85, v229, v4
	v_fma_f32 v5, v85, v233, v5
	v_fma_f32 v10, v86, v206, v10
	v_fma_f32 v11, v86, v210, v11
	v_fma_f32 v8, v86, v214, v8
	v_fma_f32 v9, v86, v218, v9
	v_fma_f32 v6, v86, v222, v6
	v_fma_f32 v7, v86, v226, v7
	v_fma_f32 v4, v86, v230, v4
	v_fma_f32 v5, v86, v234, v5
	v_fma_f32 v10, v87, v207, v10
	v_fma_f32 v11, v87, v211, v11
	v_fma_f32 v8, v87, v215, v8
	v_fma_f32 v9, v87, v219, v9
	v_fma_f32 v6, v87, v223, v6
	v_fma_f32 v7, v87, v227, v7
	v_fma_f32 v4, v87, v231, v4
	v_fma_f32 v5, v87, v235, v5
	global_load_dword v136, v[194:195], off
	v_lshl_add_u64 v[194:195], v[194:195], 0, s[0:1]
	global_load_dword v137, v[196:197], off
	v_lshl_add_u64 v[196:197], v[196:197], 0, s[0:1]
	global_load_dword v138, v[198:199], off
	v_lshl_add_u64 v[198:199], v[198:199], 0, s[0:1]
	global_load_dword v139, v[200:201], off
	v_lshl_add_u64 v[200:201], v[200:201], 0, s[0:1]
	ds_read_b128 v[204:207], v202 offset:112
	ds_read_b128 v[208:211], v202 offset:4208
	ds_read_b128 v[212:215], v202 offset:8304
	ds_read_b128 v[216:219], v202 offset:12400
	ds_read_b128 v[220:223], v202 offset:16496
	ds_read_b128 v[224:227], v202 offset:20592
	ds_read_b128 v[228:231], v202 offset:24688
	ds_read_b128 v[232:235], v202 offset:28784
	s_waitcnt vmcnt(48) lgkmcnt(8)
	v_fma_f32 v10, v88, v14, v10
	v_fma_f32 v11, v88, v18, v11
	v_fma_f32 v8, v88, v22, v8
	v_fma_f32 v9, v88, v26, v9
	v_fma_f32 v6, v88, v30, v6
	v_fma_f32 v7, v88, v34, v7
	v_fma_f32 v4, v88, v38, v4
	v_fma_f32 v5, v88, v42, v5
	v_fma_f32 v10, v89, v15, v10
	v_fma_f32 v11, v89, v19, v11
	v_fma_f32 v8, v89, v23, v8
	v_fma_f32 v9, v89, v27, v9
	v_fma_f32 v6, v89, v31, v6
	v_fma_f32 v7, v89, v35, v7
	v_fma_f32 v4, v89, v39, v4
	v_fma_f32 v5, v89, v43, v5
	v_fma_f32 v10, v90, v16, v10
	v_fma_f32 v11, v90, v20, v11
	v_fma_f32 v8, v90, v24, v8
	v_fma_f32 v9, v90, v28, v9
	v_fma_f32 v6, v90, v32, v6
	v_fma_f32 v7, v90, v36, v7
	v_fma_f32 v4, v90, v40, v4
	v_fma_f32 v5, v90, v44, v5
	v_fma_f32 v10, v91, v17, v10
	v_fma_f32 v11, v91, v21, v11
	v_fma_f32 v8, v91, v25, v8
	v_fma_f32 v9, v91, v29, v9
	v_fma_f32 v6, v91, v33, v6
	v_fma_f32 v7, v91, v37, v7
	v_fma_f32 v4, v91, v41, v4
	v_fma_f32 v5, v91, v45, v5
	global_load_dword v140, v[194:195], off
	v_lshl_add_u64 v[194:195], v[194:195], 0, s[0:1]
	global_load_dword v141, v[196:197], off
	v_lshl_add_u64 v[196:197], v[196:197], 0, s[0:1]
	global_load_dword v142, v[198:199], off
	v_lshl_add_u64 v[198:199], v[198:199], 0, s[0:1]
	global_load_dword v143, v[200:201], off
	v_lshl_add_u64 v[200:201], v[200:201], 0, s[0:1]
	ds_read_b128 v[14:17], v202 offset:128
	ds_read_b128 v[18:21], v202 offset:4224
	ds_read_b128 v[22:25], v202 offset:8320
	ds_read_b128 v[26:29], v202 offset:12416
	ds_read_b128 v[30:33], v202 offset:16512
	ds_read_b128 v[34:37], v202 offset:20608
	ds_read_b128 v[38:41], v202 offset:24704
	ds_read_b128 v[42:45], v202 offset:28800
	s_waitcnt vmcnt(48) lgkmcnt(8)
	v_fma_f32 v10, v92, v204, v10
	v_fma_f32 v11, v92, v208, v11
	v_fma_f32 v8, v92, v212, v8
	v_fma_f32 v9, v92, v216, v9
	v_fma_f32 v6, v92, v220, v6
	v_fma_f32 v7, v92, v224, v7
	v_fma_f32 v4, v92, v228, v4
	v_fma_f32 v5, v92, v232, v5
	v_fma_f32 v10, v93, v205, v10
	v_fma_f32 v11, v93, v209, v11
	v_fma_f32 v8, v93, v213, v8
	v_fma_f32 v9, v93, v217, v9
	v_fma_f32 v6, v93, v221, v6
	v_fma_f32 v7, v93, v225, v7
	v_fma_f32 v4, v93, v229, v4
	v_fma_f32 v5, v93, v233, v5
	v_fma_f32 v10, v94, v206, v10
	v_fma_f32 v11, v94, v210, v11
	v_fma_f32 v8, v94, v214, v8
	v_fma_f32 v9, v94, v218, v9
	v_fma_f32 v6, v94, v222, v6
	v_fma_f32 v7, v94, v226, v7
	v_fma_f32 v4, v94, v230, v4
	v_fma_f32 v5, v94, v234, v5
	v_fma_f32 v10, v95, v207, v10
	v_fma_f32 v11, v95, v211, v11
	v_fma_f32 v8, v95, v215, v8
	v_fma_f32 v9, v95, v219, v9
	v_fma_f32 v6, v95, v223, v6
	v_fma_f32 v7, v95, v227, v7
	v_fma_f32 v4, v95, v231, v4
	v_fma_f32 v5, v95, v235, v5
	global_load_dword v144, v[194:195], off
	v_lshl_add_u64 v[194:195], v[194:195], 0, s[0:1]
	global_load_dword v145, v[196:197], off
	v_lshl_add_u64 v[196:197], v[196:197], 0, s[0:1]
	global_load_dword v146, v[198:199], off
	v_lshl_add_u64 v[198:199], v[198:199], 0, s[0:1]
	global_load_dword v147, v[200:201], off
	v_lshl_add_u64 v[200:201], v[200:201], 0, s[0:1]
	ds_read_b128 v[204:207], v202 offset:144
	ds_read_b128 v[208:211], v202 offset:4240
	ds_read_b128 v[212:215], v202 offset:8336
	ds_read_b128 v[216:219], v202 offset:12432
	ds_read_b128 v[220:223], v202 offset:16528
	ds_read_b128 v[224:227], v202 offset:20624
	ds_read_b128 v[228:231], v202 offset:24720
	ds_read_b128 v[232:235], v202 offset:28816
	s_waitcnt vmcnt(48) lgkmcnt(8)
	v_fma_f32 v10, v96, v14, v10
	v_fma_f32 v11, v96, v18, v11
	v_fma_f32 v8, v96, v22, v8
	v_fma_f32 v9, v96, v26, v9
	v_fma_f32 v6, v96, v30, v6
	v_fma_f32 v7, v96, v34, v7
	v_fma_f32 v4, v96, v38, v4
	v_fma_f32 v5, v96, v42, v5
	v_fma_f32 v10, v97, v15, v10
	v_fma_f32 v11, v97, v19, v11
	v_fma_f32 v8, v97, v23, v8
	v_fma_f32 v9, v97, v27, v9
	v_fma_f32 v6, v97, v31, v6
	v_fma_f32 v7, v97, v35, v7
	v_fma_f32 v4, v97, v39, v4
	v_fma_f32 v5, v97, v43, v5
	v_fma_f32 v10, v98, v16, v10
	v_fma_f32 v11, v98, v20, v11
	v_fma_f32 v8, v98, v24, v8
	v_fma_f32 v9, v98, v28, v9
	v_fma_f32 v6, v98, v32, v6
	v_fma_f32 v7, v98, v36, v7
	v_fma_f32 v4, v98, v40, v4
	v_fma_f32 v5, v98, v44, v5
	v_fma_f32 v10, v99, v17, v10
	v_fma_f32 v11, v99, v21, v11
	v_fma_f32 v8, v99, v25, v8
	v_fma_f32 v9, v99, v29, v9
	v_fma_f32 v6, v99, v33, v6
	v_fma_f32 v7, v99, v37, v7
	v_fma_f32 v4, v99, v41, v4
	v_fma_f32 v5, v99, v45, v5
	global_load_dword v148, v[194:195], off
	v_lshl_add_u64 v[194:195], v[194:195], 0, s[0:1]
	global_load_dword v149, v[196:197], off
	v_lshl_add_u64 v[196:197], v[196:197], 0, s[0:1]
	global_load_dword v150, v[198:199], off
	v_lshl_add_u64 v[198:199], v[198:199], 0, s[0:1]
	global_load_dword v151, v[200:201], off
	v_lshl_add_u64 v[200:201], v[200:201], 0, s[0:1]
	ds_read_b128 v[14:17], v202 offset:160
	ds_read_b128 v[18:21], v202 offset:4256
	ds_read_b128 v[22:25], v202 offset:8352
	ds_read_b128 v[26:29], v202 offset:12448
	ds_read_b128 v[30:33], v202 offset:16544
	ds_read_b128 v[34:37], v202 offset:20640
	ds_read_b128 v[38:41], v202 offset:24736
	ds_read_b128 v[42:45], v202 offset:28832
	s_waitcnt vmcnt(48) lgkmcnt(8)
	v_fma_f32 v10, v100, v204, v10
	v_fma_f32 v11, v100, v208, v11
	v_fma_f32 v8, v100, v212, v8
	v_fma_f32 v9, v100, v216, v9
	v_fma_f32 v6, v100, v220, v6
	v_fma_f32 v7, v100, v224, v7
	v_fma_f32 v4, v100, v228, v4
	v_fma_f32 v5, v100, v232, v5
	v_fma_f32 v10, v101, v205, v10
	v_fma_f32 v11, v101, v209, v11
	v_fma_f32 v8, v101, v213, v8
	v_fma_f32 v9, v101, v217, v9
	v_fma_f32 v6, v101, v221, v6
	v_fma_f32 v7, v101, v225, v7
	v_fma_f32 v4, v101, v229, v4
	v_fma_f32 v5, v101, v233, v5
	v_fma_f32 v10, v102, v206, v10
	v_fma_f32 v11, v102, v210, v11
	v_fma_f32 v8, v102, v214, v8
	v_fma_f32 v9, v102, v218, v9
	v_fma_f32 v6, v102, v222, v6
	v_fma_f32 v7, v102, v226, v7
	v_fma_f32 v4, v102, v230, v4
	v_fma_f32 v5, v102, v234, v5
	v_fma_f32 v10, v103, v207, v10
	v_fma_f32 v11, v103, v211, v11
	v_fma_f32 v8, v103, v215, v8
	v_fma_f32 v9, v103, v219, v9
	v_fma_f32 v6, v103, v223, v6
	v_fma_f32 v7, v103, v227, v7
	v_fma_f32 v4, v103, v231, v4
	v_fma_f32 v5, v103, v235, v5
	global_load_dword v152, v[194:195], off
	v_lshl_add_u64 v[194:195], v[194:195], 0, s[0:1]
	global_load_dword v153, v[196:197], off
	v_lshl_add_u64 v[196:197], v[196:197], 0, s[0:1]
	global_load_dword v154, v[198:199], off
	v_lshl_add_u64 v[198:199], v[198:199], 0, s[0:1]
	global_load_dword v155, v[200:201], off
	v_lshl_add_u64 v[200:201], v[200:201], 0, s[0:1]
	ds_read_b128 v[204:207], v202 offset:176
	ds_read_b128 v[208:211], v202 offset:4272
	ds_read_b128 v[212:215], v202 offset:8368
	ds_read_b128 v[216:219], v202 offset:12464
	ds_read_b128 v[220:223], v202 offset:16560
	ds_read_b128 v[224:227], v202 offset:20656
	ds_read_b128 v[228:231], v202 offset:24752
	ds_read_b128 v[232:235], v202 offset:28848
	s_waitcnt vmcnt(48) lgkmcnt(8)
	v_fma_f32 v10, v104, v14, v10
	v_fma_f32 v11, v104, v18, v11
	v_fma_f32 v8, v104, v22, v8
	v_fma_f32 v9, v104, v26, v9
	v_fma_f32 v6, v104, v30, v6
	v_fma_f32 v7, v104, v34, v7
	v_fma_f32 v4, v104, v38, v4
	v_fma_f32 v5, v104, v42, v5
	v_fma_f32 v10, v105, v15, v10
	v_fma_f32 v11, v105, v19, v11
	v_fma_f32 v8, v105, v23, v8
	v_fma_f32 v9, v105, v27, v9
	v_fma_f32 v6, v105, v31, v6
	v_fma_f32 v7, v105, v35, v7
	v_fma_f32 v4, v105, v39, v4
	v_fma_f32 v5, v105, v43, v5
	v_fma_f32 v10, v106, v16, v10
	v_fma_f32 v11, v106, v20, v11
	v_fma_f32 v8, v106, v24, v8
	v_fma_f32 v9, v106, v28, v9
	v_fma_f32 v6, v106, v32, v6
	v_fma_f32 v7, v106, v36, v7
	v_fma_f32 v4, v106, v40, v4
	v_fma_f32 v5, v106, v44, v5
	v_fma_f32 v10, v107, v17, v10
	v_fma_f32 v11, v107, v21, v11
	v_fma_f32 v8, v107, v25, v8
	v_fma_f32 v9, v107, v29, v9
	v_fma_f32 v6, v107, v33, v6
	v_fma_f32 v7, v107, v37, v7
	v_fma_f32 v4, v107, v41, v4
	v_fma_f32 v5, v107, v45, v5
	global_load_dword v156, v[194:195], off
	v_lshl_add_u64 v[194:195], v[194:195], 0, s[0:1]
	global_load_dword v157, v[196:197], off
	v_lshl_add_u64 v[196:197], v[196:197], 0, s[0:1]
	global_load_dword v158, v[198:199], off
	v_lshl_add_u64 v[198:199], v[198:199], 0, s[0:1]
	global_load_dword v159, v[200:201], off
	v_lshl_add_u64 v[200:201], v[200:201], 0, s[0:1]
	ds_read_b128 v[14:17], v202 offset:192
	ds_read_b128 v[18:21], v202 offset:4288
	ds_read_b128 v[22:25], v202 offset:8384
	ds_read_b128 v[26:29], v202 offset:12480
	ds_read_b128 v[30:33], v202 offset:16576
	ds_read_b128 v[34:37], v202 offset:20672
	ds_read_b128 v[38:41], v202 offset:24768
	ds_read_b128 v[42:45], v202 offset:28864
	s_waitcnt vmcnt(48) lgkmcnt(8)
	v_fma_f32 v10, v108, v204, v10
	v_fma_f32 v11, v108, v208, v11
	v_fma_f32 v8, v108, v212, v8
	v_fma_f32 v9, v108, v216, v9
	v_fma_f32 v6, v108, v220, v6
	v_fma_f32 v7, v108, v224, v7
	v_fma_f32 v4, v108, v228, v4
	v_fma_f32 v5, v108, v232, v5
	v_fma_f32 v10, v109, v205, v10
	v_fma_f32 v11, v109, v209, v11
	v_fma_f32 v8, v109, v213, v8
	v_fma_f32 v9, v109, v217, v9
	v_fma_f32 v6, v109, v221, v6
	v_fma_f32 v7, v109, v225, v7
	v_fma_f32 v4, v109, v229, v4
	v_fma_f32 v5, v109, v233, v5
	v_fma_f32 v10, v110, v206, v10
	v_fma_f32 v11, v110, v210, v11
	v_fma_f32 v8, v110, v214, v8
	v_fma_f32 v9, v110, v218, v9
	v_fma_f32 v6, v110, v222, v6
	v_fma_f32 v7, v110, v226, v7
	v_fma_f32 v4, v110, v230, v4
	v_fma_f32 v5, v110, v234, v5
	v_fma_f32 v10, v111, v207, v10
	v_fma_f32 v11, v111, v211, v11
	v_fma_f32 v8, v111, v215, v8
	v_fma_f32 v9, v111, v219, v9
	v_fma_f32 v6, v111, v223, v6
	v_fma_f32 v7, v111, v227, v7
	v_fma_f32 v4, v111, v231, v4
	v_fma_f32 v5, v111, v235, v5
	global_load_dword v160, v[194:195], off
	v_lshl_add_u64 v[194:195], v[194:195], 0, s[0:1]
	global_load_dword v161, v[196:197], off
	v_lshl_add_u64 v[196:197], v[196:197], 0, s[0:1]
	global_load_dword v162, v[198:199], off
	v_lshl_add_u64 v[198:199], v[198:199], 0, s[0:1]
	global_load_dword v163, v[200:201], off
	v_lshl_add_u64 v[200:201], v[200:201], 0, s[0:1]
	ds_read_b128 v[204:207], v202 offset:208
	ds_read_b128 v[208:211], v202 offset:4304
	ds_read_b128 v[212:215], v202 offset:8400
	ds_read_b128 v[216:219], v202 offset:12496
	ds_read_b128 v[220:223], v202 offset:16592
	ds_read_b128 v[224:227], v202 offset:20688
	ds_read_b128 v[228:231], v202 offset:24784
	ds_read_b128 v[232:235], v202 offset:28880
	s_waitcnt vmcnt(48) lgkmcnt(8)
	v_fma_f32 v10, v112, v14, v10
	v_fma_f32 v11, v112, v18, v11
	v_fma_f32 v8, v112, v22, v8
	v_fma_f32 v9, v112, v26, v9
	v_fma_f32 v6, v112, v30, v6
	v_fma_f32 v7, v112, v34, v7
	v_fma_f32 v4, v112, v38, v4
	v_fma_f32 v5, v112, v42, v5
	v_fma_f32 v10, v113, v15, v10
	v_fma_f32 v11, v113, v19, v11
	v_fma_f32 v8, v113, v23, v8
	v_fma_f32 v9, v113, v27, v9
	v_fma_f32 v6, v113, v31, v6
	v_fma_f32 v7, v113, v35, v7
	v_fma_f32 v4, v113, v39, v4
	v_fma_f32 v5, v113, v43, v5
	v_fma_f32 v10, v114, v16, v10
	v_fma_f32 v11, v114, v20, v11
	v_fma_f32 v8, v114, v24, v8
	v_fma_f32 v9, v114, v28, v9
	v_fma_f32 v6, v114, v32, v6
	v_fma_f32 v7, v114, v36, v7
	v_fma_f32 v4, v114, v40, v4
	v_fma_f32 v5, v114, v44, v5
	v_fma_f32 v10, v115, v17, v10
	v_fma_f32 v11, v115, v21, v11
	v_fma_f32 v8, v115, v25, v8
	v_fma_f32 v9, v115, v29, v9
	v_fma_f32 v6, v115, v33, v6
	v_fma_f32 v7, v115, v37, v7
	v_fma_f32 v4, v115, v41, v4
	v_fma_f32 v5, v115, v45, v5
	global_load_dword v164, v[194:195], off
	v_lshl_add_u64 v[194:195], v[194:195], 0, s[0:1]
	global_load_dword v165, v[196:197], off
	v_lshl_add_u64 v[196:197], v[196:197], 0, s[0:1]
	global_load_dword v166, v[198:199], off
	v_lshl_add_u64 v[198:199], v[198:199], 0, s[0:1]
	global_load_dword v167, v[200:201], off
	v_lshl_add_u64 v[200:201], v[200:201], 0, s[0:1]
	ds_read_b128 v[14:17], v202 offset:224
	ds_read_b128 v[18:21], v202 offset:4320
	ds_read_b128 v[22:25], v202 offset:8416
	ds_read_b128 v[26:29], v202 offset:12512
	ds_read_b128 v[30:33], v202 offset:16608
	ds_read_b128 v[34:37], v202 offset:20704
	ds_read_b128 v[38:41], v202 offset:24800
	ds_read_b128 v[42:45], v202 offset:28896
	s_waitcnt vmcnt(48) lgkmcnt(8)
	v_fma_f32 v10, v116, v204, v10
	v_fma_f32 v11, v116, v208, v11
	v_fma_f32 v8, v116, v212, v8
	v_fma_f32 v9, v116, v216, v9
	v_fma_f32 v6, v116, v220, v6
	v_fma_f32 v7, v116, v224, v7
	v_fma_f32 v4, v116, v228, v4
	v_fma_f32 v5, v116, v232, v5
	v_fma_f32 v10, v117, v205, v10
	v_fma_f32 v11, v117, v209, v11
	v_fma_f32 v8, v117, v213, v8
	v_fma_f32 v9, v117, v217, v9
	v_fma_f32 v6, v117, v221, v6
	v_fma_f32 v7, v117, v225, v7
	v_fma_f32 v4, v117, v229, v4
	v_fma_f32 v5, v117, v233, v5
	v_fma_f32 v10, v118, v206, v10
	v_fma_f32 v11, v118, v210, v11
	v_fma_f32 v8, v118, v214, v8
	v_fma_f32 v9, v118, v218, v9
	v_fma_f32 v6, v118, v222, v6
	v_fma_f32 v7, v118, v226, v7
	v_fma_f32 v4, v118, v230, v4
	v_fma_f32 v5, v118, v234, v5
	v_fma_f32 v10, v119, v207, v10
	v_fma_f32 v11, v119, v211, v11
	v_fma_f32 v8, v119, v215, v8
	v_fma_f32 v9, v119, v219, v9
	v_fma_f32 v6, v119, v223, v6
	v_fma_f32 v7, v119, v227, v7
	v_fma_f32 v4, v119, v231, v4
	v_fma_f32 v5, v119, v235, v5
	global_load_dword v168, v[194:195], off
	v_lshl_add_u64 v[194:195], v[194:195], 0, s[0:1]
	global_load_dword v169, v[196:197], off
	v_lshl_add_u64 v[196:197], v[196:197], 0, s[0:1]
	global_load_dword v170, v[198:199], off
	v_lshl_add_u64 v[198:199], v[198:199], 0, s[0:1]
	global_load_dword v171, v[200:201], off
	v_lshl_add_u64 v[200:201], v[200:201], 0, s[0:1]
	ds_read_b128 v[204:207], v202 offset:240
	ds_read_b128 v[208:211], v202 offset:4336
	ds_read_b128 v[212:215], v202 offset:8432
	ds_read_b128 v[216:219], v202 offset:12528
	ds_read_b128 v[220:223], v202 offset:16624
	ds_read_b128 v[224:227], v202 offset:20720
	ds_read_b128 v[228:231], v202 offset:24816
	ds_read_b128 v[232:235], v202 offset:28912
	s_waitcnt vmcnt(48) lgkmcnt(8)
	v_fma_f32 v10, v120, v14, v10
	v_fma_f32 v11, v120, v18, v11
	v_fma_f32 v8, v120, v22, v8
	v_fma_f32 v9, v120, v26, v9
	v_fma_f32 v6, v120, v30, v6
	v_fma_f32 v7, v120, v34, v7
	v_fma_f32 v4, v120, v38, v4
	v_fma_f32 v5, v120, v42, v5
	v_fma_f32 v10, v121, v15, v10
	v_fma_f32 v11, v121, v19, v11
	v_fma_f32 v8, v121, v23, v8
	v_fma_f32 v9, v121, v27, v9
	v_fma_f32 v6, v121, v31, v6
	v_fma_f32 v7, v121, v35, v7
	v_fma_f32 v4, v121, v39, v4
	v_fma_f32 v5, v121, v43, v5
	v_fma_f32 v10, v122, v16, v10
	v_fma_f32 v11, v122, v20, v11
	v_fma_f32 v8, v122, v24, v8
	v_fma_f32 v9, v122, v28, v9
	v_fma_f32 v6, v122, v32, v6
	v_fma_f32 v7, v122, v36, v7
	v_fma_f32 v4, v122, v40, v4
	v_fma_f32 v5, v122, v44, v5
	v_fma_f32 v10, v123, v17, v10
	v_fma_f32 v11, v123, v21, v11
	v_fma_f32 v8, v123, v25, v8
	v_fma_f32 v9, v123, v29, v9
	v_fma_f32 v6, v123, v33, v6
	v_fma_f32 v7, v123, v37, v7
	v_fma_f32 v4, v123, v41, v4
	v_fma_f32 v5, v123, v45, v5
	global_load_dword v172, v[194:195], off
	v_lshl_add_u64 v[194:195], v[194:195], 0, s[0:1]
	global_load_dword v173, v[196:197], off
	v_lshl_add_u64 v[196:197], v[196:197], 0, s[0:1]
	global_load_dword v174, v[198:199], off
	v_lshl_add_u64 v[198:199], v[198:199], 0, s[0:1]
	global_load_dword v175, v[200:201], off
	v_lshl_add_u64 v[200:201], v[200:201], 0, s[0:1]
	ds_read_b128 v[14:17], v202 offset:256
	ds_read_b128 v[18:21], v202 offset:4352
	ds_read_b128 v[22:25], v202 offset:8448
	ds_read_b128 v[26:29], v202 offset:12544
	ds_read_b128 v[30:33], v202 offset:16640
	ds_read_b128 v[34:37], v202 offset:20736
	ds_read_b128 v[38:41], v202 offset:24832
	ds_read_b128 v[42:45], v202 offset:28928
	s_waitcnt vmcnt(48) lgkmcnt(8)
	v_fma_f32 v10, v124, v204, v10
	v_fma_f32 v11, v124, v208, v11
	v_fma_f32 v8, v124, v212, v8
	v_fma_f32 v9, v124, v216, v9
	v_fma_f32 v6, v124, v220, v6
	v_fma_f32 v7, v124, v224, v7
	v_fma_f32 v4, v124, v228, v4
	v_fma_f32 v5, v124, v232, v5
	v_fma_f32 v10, v125, v205, v10
	v_fma_f32 v11, v125, v209, v11
	v_fma_f32 v8, v125, v213, v8
	v_fma_f32 v9, v125, v217, v9
	v_fma_f32 v6, v125, v221, v6
	v_fma_f32 v7, v125, v225, v7
	v_fma_f32 v4, v125, v229, v4
	v_fma_f32 v5, v125, v233, v5
	v_fma_f32 v10, v126, v206, v10
	v_fma_f32 v11, v126, v210, v11
	v_fma_f32 v8, v126, v214, v8
	v_fma_f32 v9, v126, v218, v9
	v_fma_f32 v6, v126, v222, v6
	v_fma_f32 v7, v126, v226, v7
	v_fma_f32 v4, v126, v230, v4
	v_fma_f32 v5, v126, v234, v5
	v_fma_f32 v10, v127, v207, v10
	v_fma_f32 v11, v127, v211, v11
	v_fma_f32 v8, v127, v215, v8
	v_fma_f32 v9, v127, v219, v9
	v_fma_f32 v6, v127, v223, v6
	v_fma_f32 v7, v127, v227, v7
	v_fma_f32 v4, v127, v231, v4
	v_fma_f32 v5, v127, v235, v5
	global_load_dword v176, v[194:195], off
	v_lshl_add_u64 v[194:195], v[194:195], 0, s[0:1]
	global_load_dword v177, v[196:197], off
	v_lshl_add_u64 v[196:197], v[196:197], 0, s[0:1]
	global_load_dword v178, v[198:199], off
	v_lshl_add_u64 v[198:199], v[198:199], 0, s[0:1]
	global_load_dword v180, v[200:201], off
	v_lshl_add_u64 v[200:201], v[200:201], 0, s[0:1]
	ds_read_b128 v[204:207], v202 offset:272
	ds_read_b128 v[208:211], v202 offset:4368
	ds_read_b128 v[212:215], v202 offset:8464
	ds_read_b128 v[216:219], v202 offset:12560
	ds_read_b128 v[220:223], v202 offset:16656
	ds_read_b128 v[224:227], v202 offset:20752
	ds_read_b128 v[228:231], v202 offset:24848
	ds_read_b128 v[232:235], v202 offset:28944
	s_waitcnt vmcnt(48) lgkmcnt(8)
	v_fma_f32 v10, v128, v14, v10
	v_fma_f32 v11, v128, v18, v11
	v_fma_f32 v8, v128, v22, v8
	v_fma_f32 v9, v128, v26, v9
	v_fma_f32 v6, v128, v30, v6
	v_fma_f32 v7, v128, v34, v7
	v_fma_f32 v4, v128, v38, v4
	v_fma_f32 v5, v128, v42, v5
	v_fma_f32 v10, v129, v15, v10
	v_fma_f32 v11, v129, v19, v11
	v_fma_f32 v8, v129, v23, v8
	v_fma_f32 v9, v129, v27, v9
	v_fma_f32 v6, v129, v31, v6
	v_fma_f32 v7, v129, v35, v7
	v_fma_f32 v4, v129, v39, v4
	v_fma_f32 v5, v129, v43, v5
	v_fma_f32 v10, v130, v16, v10
	v_fma_f32 v11, v130, v20, v11
	v_fma_f32 v8, v130, v24, v8
	v_fma_f32 v9, v130, v28, v9
	v_fma_f32 v6, v130, v32, v6
	v_fma_f32 v7, v130, v36, v7
	v_fma_f32 v4, v130, v40, v4
	v_fma_f32 v5, v130, v44, v5
	v_fma_f32 v10, v131, v17, v10
	v_fma_f32 v11, v131, v21, v11
	v_fma_f32 v8, v131, v25, v8
	v_fma_f32 v9, v131, v29, v9
	v_fma_f32 v6, v131, v33, v6
	v_fma_f32 v7, v131, v37, v7
	v_fma_f32 v4, v131, v41, v4
	v_fma_f32 v5, v131, v45, v5
	global_load_dword v181, v[194:195], off
	v_lshl_add_u64 v[194:195], v[194:195], 0, s[0:1]
	global_load_dword v182, v[196:197], off
	v_lshl_add_u64 v[196:197], v[196:197], 0, s[0:1]
	global_load_dword v183, v[198:199], off
	v_lshl_add_u64 v[198:199], v[198:199], 0, s[0:1]
	global_load_dword v184, v[200:201], off
	v_lshl_add_u64 v[200:201], v[200:201], 0, s[0:1]
	ds_read_b128 v[14:17], v202 offset:288
	ds_read_b128 v[18:21], v202 offset:4384
	ds_read_b128 v[22:25], v202 offset:8480
	ds_read_b128 v[26:29], v202 offset:12576
	ds_read_b128 v[30:33], v202 offset:16672
	ds_read_b128 v[34:37], v202 offset:20768
	ds_read_b128 v[38:41], v202 offset:24864
	ds_read_b128 v[42:45], v202 offset:28960
	s_waitcnt vmcnt(48) lgkmcnt(8)
	v_fma_f32 v10, v132, v204, v10
	v_fma_f32 v11, v132, v208, v11
	v_fma_f32 v8, v132, v212, v8
	v_fma_f32 v9, v132, v216, v9
	v_fma_f32 v6, v132, v220, v6
	v_fma_f32 v7, v132, v224, v7
	v_fma_f32 v4, v132, v228, v4
	v_fma_f32 v5, v132, v232, v5
	v_fma_f32 v10, v133, v205, v10
	v_fma_f32 v11, v133, v209, v11
	v_fma_f32 v8, v133, v213, v8
	v_fma_f32 v9, v133, v217, v9
	v_fma_f32 v6, v133, v221, v6
	v_fma_f32 v7, v133, v225, v7
	v_fma_f32 v4, v133, v229, v4
	v_fma_f32 v5, v133, v233, v5
	v_fma_f32 v10, v134, v206, v10
	v_fma_f32 v11, v134, v210, v11
	v_fma_f32 v8, v134, v214, v8
	v_fma_f32 v9, v134, v218, v9
	v_fma_f32 v6, v134, v222, v6
	v_fma_f32 v7, v134, v226, v7
	v_fma_f32 v4, v134, v230, v4
	v_fma_f32 v5, v134, v234, v5
	v_fma_f32 v10, v135, v207, v10
	v_fma_f32 v11, v135, v211, v11
	v_fma_f32 v8, v135, v215, v8
	v_fma_f32 v9, v135, v219, v9
	v_fma_f32 v6, v135, v223, v6
	v_fma_f32 v7, v135, v227, v7
	v_fma_f32 v4, v135, v231, v4
	v_fma_f32 v5, v135, v235, v5
	global_load_dword v185, v[194:195], off
	v_lshl_add_u64 v[194:195], v[194:195], 0, s[0:1]
	global_load_dword v186, v[196:197], off
	v_lshl_add_u64 v[196:197], v[196:197], 0, s[0:1]
	global_load_dword v187, v[198:199], off
	v_lshl_add_u64 v[198:199], v[198:199], 0, s[0:1]
	global_load_dword v188, v[200:201], off
	v_lshl_add_u64 v[200:201], v[200:201], 0, s[0:1]
	ds_read_b128 v[204:207], v202 offset:304
	ds_read_b128 v[208:211], v202 offset:4400
	ds_read_b128 v[212:215], v202 offset:8496
	ds_read_b128 v[216:219], v202 offset:12592
	ds_read_b128 v[220:223], v202 offset:16688
	ds_read_b128 v[224:227], v202 offset:20784
	ds_read_b128 v[228:231], v202 offset:24880
	ds_read_b128 v[232:235], v202 offset:28976
	s_waitcnt vmcnt(48) lgkmcnt(8)
	v_fma_f32 v10, v136, v14, v10
	v_fma_f32 v11, v136, v18, v11
	v_fma_f32 v8, v136, v22, v8
	v_fma_f32 v9, v136, v26, v9
	v_fma_f32 v6, v136, v30, v6
	v_fma_f32 v7, v136, v34, v7
	v_fma_f32 v4, v136, v38, v4
	v_fma_f32 v5, v136, v42, v5
	v_fma_f32 v10, v137, v15, v10
	v_fma_f32 v11, v137, v19, v11
	v_fma_f32 v8, v137, v23, v8
	v_fma_f32 v9, v137, v27, v9
	v_fma_f32 v6, v137, v31, v6
	v_fma_f32 v7, v137, v35, v7
	v_fma_f32 v4, v137, v39, v4
	v_fma_f32 v5, v137, v43, v5
	v_fma_f32 v10, v138, v16, v10
	v_fma_f32 v11, v138, v20, v11
	v_fma_f32 v8, v138, v24, v8
	v_fma_f32 v9, v138, v28, v9
	v_fma_f32 v6, v138, v32, v6
	v_fma_f32 v7, v138, v36, v7
	v_fma_f32 v4, v138, v40, v4
	v_fma_f32 v5, v138, v44, v5
	v_fma_f32 v10, v139, v17, v10
	v_fma_f32 v11, v139, v21, v11
	v_fma_f32 v8, v139, v25, v8
	v_fma_f32 v9, v139, v29, v9
	v_fma_f32 v6, v139, v33, v6
	v_fma_f32 v7, v139, v37, v7
	v_fma_f32 v4, v139, v41, v4
	v_fma_f32 v5, v139, v45, v5
	global_load_dword v189, v[194:195], off
	global_load_dword v190, v[196:197], off
	global_load_dword v191, v[198:199], off
	global_load_dword v192, v[200:201], off
	ds_read_b128 v[14:17], v202 offset:320
	ds_read_b128 v[18:21], v202 offset:4416
	ds_read_b128 v[22:25], v202 offset:8512
	ds_read_b128 v[26:29], v202 offset:12608
	ds_read_b128 v[30:33], v202 offset:16704
	ds_read_b128 v[34:37], v202 offset:20800
	ds_read_b128 v[38:41], v202 offset:24896
	ds_read_b128 v[42:45], v202 offset:28992
	s_waitcnt vmcnt(48) lgkmcnt(8)
	v_fma_f32 v10, v140, v204, v10
	v_fma_f32 v11, v140, v208, v11
	v_fma_f32 v8, v140, v212, v8
	v_fma_f32 v9, v140, v216, v9
	v_fma_f32 v6, v140, v220, v6
	v_fma_f32 v7, v140, v224, v7
	v_fma_f32 v4, v140, v228, v4
	v_fma_f32 v5, v140, v232, v5
	v_fma_f32 v10, v141, v205, v10
	v_fma_f32 v11, v141, v209, v11
	v_fma_f32 v8, v141, v213, v8
	v_fma_f32 v9, v141, v217, v9
	v_fma_f32 v6, v141, v221, v6
	v_fma_f32 v7, v141, v225, v7
	v_fma_f32 v4, v141, v229, v4
	v_fma_f32 v5, v141, v233, v5
	v_fma_f32 v10, v142, v206, v10
	v_fma_f32 v11, v142, v210, v11
	v_fma_f32 v8, v142, v214, v8
	v_fma_f32 v9, v142, v218, v9
	v_fma_f32 v6, v142, v222, v6
	v_fma_f32 v7, v142, v226, v7
	v_fma_f32 v4, v142, v230, v4
	v_fma_f32 v5, v142, v234, v5
	v_fma_f32 v10, v143, v207, v10
	v_fma_f32 v11, v143, v211, v11
	v_fma_f32 v8, v143, v215, v8
	v_fma_f32 v9, v143, v219, v9
	v_fma_f32 v6, v143, v223, v6
	v_fma_f32 v7, v143, v227, v7
	v_fma_f32 v4, v143, v231, v4
	v_fma_f32 v5, v143, v235, v5
	ds_read_b128 v[204:207], v202 offset:336
	ds_read_b128 v[208:211], v202 offset:4432
	ds_read_b128 v[212:215], v202 offset:8528
	ds_read_b128 v[216:219], v202 offset:12624
	ds_read_b128 v[220:223], v202 offset:16720
	ds_read_b128 v[224:227], v202 offset:20816
	ds_read_b128 v[228:231], v202 offset:24912
	ds_read_b128 v[232:235], v202 offset:29008
	s_waitcnt vmcnt(44) lgkmcnt(8)
	v_fma_f32 v10, v144, v14, v10
	v_fma_f32 v11, v144, v18, v11
	v_fma_f32 v8, v144, v22, v8
	v_fma_f32 v9, v144, v26, v9
	v_fma_f32 v6, v144, v30, v6
	v_fma_f32 v7, v144, v34, v7
	v_fma_f32 v4, v144, v38, v4
	v_fma_f32 v5, v144, v42, v5
	v_fma_f32 v10, v145, v15, v10
	v_fma_f32 v11, v145, v19, v11
	v_fma_f32 v8, v145, v23, v8
	v_fma_f32 v9, v145, v27, v9
	v_fma_f32 v6, v145, v31, v6
	v_fma_f32 v7, v145, v35, v7
	v_fma_f32 v4, v145, v39, v4
	v_fma_f32 v5, v145, v43, v5
	v_fma_f32 v10, v146, v16, v10
	v_fma_f32 v11, v146, v20, v11
	v_fma_f32 v8, v146, v24, v8
	v_fma_f32 v9, v146, v28, v9
	v_fma_f32 v6, v146, v32, v6
	v_fma_f32 v7, v146, v36, v7
	v_fma_f32 v4, v146, v40, v4
	v_fma_f32 v5, v146, v44, v5
	v_fma_f32 v10, v147, v17, v10
	v_fma_f32 v11, v147, v21, v11
	v_fma_f32 v8, v147, v25, v8
	v_fma_f32 v9, v147, v29, v9
	v_fma_f32 v6, v147, v33, v6
	v_fma_f32 v7, v147, v37, v7
	v_fma_f32 v4, v147, v41, v4
	v_fma_f32 v5, v147, v45, v5
	ds_read_b128 v[14:17], v202 offset:352
	ds_read_b128 v[18:21], v202 offset:4448
	ds_read_b128 v[22:25], v202 offset:8544
	ds_read_b128 v[26:29], v202 offset:12640
	ds_read_b128 v[30:33], v202 offset:16736
	ds_read_b128 v[34:37], v202 offset:20832
	ds_read_b128 v[38:41], v202 offset:24928
	ds_read_b128 v[42:45], v202 offset:29024
	s_waitcnt vmcnt(40) lgkmcnt(8)
	v_fma_f32 v10, v148, v204, v10
	v_fma_f32 v11, v148, v208, v11
	v_fma_f32 v8, v148, v212, v8
	v_fma_f32 v9, v148, v216, v9
	v_fma_f32 v6, v148, v220, v6
	v_fma_f32 v7, v148, v224, v7
	v_fma_f32 v4, v148, v228, v4
	v_fma_f32 v5, v148, v232, v5
	v_fma_f32 v10, v149, v205, v10
	v_fma_f32 v11, v149, v209, v11
	v_fma_f32 v8, v149, v213, v8
	v_fma_f32 v9, v149, v217, v9
	v_fma_f32 v6, v149, v221, v6
	v_fma_f32 v7, v149, v225, v7
	v_fma_f32 v4, v149, v229, v4
	v_fma_f32 v5, v149, v233, v5
	v_fma_f32 v10, v150, v206, v10
	v_fma_f32 v11, v150, v210, v11
	v_fma_f32 v8, v150, v214, v8
	v_fma_f32 v9, v150, v218, v9
	v_fma_f32 v6, v150, v222, v6
	v_fma_f32 v7, v150, v226, v7
	v_fma_f32 v4, v150, v230, v4
	v_fma_f32 v5, v150, v234, v5
	v_fma_f32 v10, v151, v207, v10
	v_fma_f32 v11, v151, v211, v11
	v_fma_f32 v8, v151, v215, v8
	v_fma_f32 v9, v151, v219, v9
	v_fma_f32 v6, v151, v223, v6
	v_fma_f32 v7, v151, v227, v7
	v_fma_f32 v4, v151, v231, v4
	v_fma_f32 v5, v151, v235, v5
	ds_read_b128 v[204:207], v202 offset:368
	ds_read_b128 v[208:211], v202 offset:4464
	ds_read_b128 v[212:215], v202 offset:8560
	ds_read_b128 v[216:219], v202 offset:12656
	ds_read_b128 v[220:223], v202 offset:16752
	ds_read_b128 v[224:227], v202 offset:20848
	ds_read_b128 v[228:231], v202 offset:24944
	ds_read_b128 v[232:235], v202 offset:29040
	s_waitcnt vmcnt(36) lgkmcnt(8)
	v_fma_f32 v10, v152, v14, v10
	v_fma_f32 v11, v152, v18, v11
	v_fma_f32 v8, v152, v22, v8
	v_fma_f32 v9, v152, v26, v9
	v_fma_f32 v6, v152, v30, v6
	v_fma_f32 v7, v152, v34, v7
	v_fma_f32 v4, v152, v38, v4
	v_fma_f32 v5, v152, v42, v5
	v_fma_f32 v10, v153, v15, v10
	v_fma_f32 v11, v153, v19, v11
	v_fma_f32 v8, v153, v23, v8
	v_fma_f32 v9, v153, v27, v9
	v_fma_f32 v6, v153, v31, v6
	v_fma_f32 v7, v153, v35, v7
	v_fma_f32 v4, v153, v39, v4
	v_fma_f32 v5, v153, v43, v5
	v_fma_f32 v10, v154, v16, v10
	v_fma_f32 v11, v154, v20, v11
	v_fma_f32 v8, v154, v24, v8
	v_fma_f32 v9, v154, v28, v9
	v_fma_f32 v6, v154, v32, v6
	v_fma_f32 v7, v154, v36, v7
	v_fma_f32 v4, v154, v40, v4
	v_fma_f32 v5, v154, v44, v5
	v_fma_f32 v10, v155, v17, v10
	v_fma_f32 v11, v155, v21, v11
	v_fma_f32 v8, v155, v25, v8
	v_fma_f32 v9, v155, v29, v9
	v_fma_f32 v6, v155, v33, v6
	v_fma_f32 v7, v155, v37, v7
	v_fma_f32 v4, v155, v41, v4
	v_fma_f32 v5, v155, v45, v5
	ds_read_b128 v[14:17], v202 offset:384
	ds_read_b128 v[18:21], v202 offset:4480
	ds_read_b128 v[22:25], v202 offset:8576
	ds_read_b128 v[26:29], v202 offset:12672
	ds_read_b128 v[30:33], v202 offset:16768
	ds_read_b128 v[34:37], v202 offset:20864
	ds_read_b128 v[38:41], v202 offset:24960
	ds_read_b128 v[42:45], v202 offset:29056
	s_waitcnt vmcnt(32) lgkmcnt(8)
	v_fma_f32 v10, v156, v204, v10
	v_fma_f32 v11, v156, v208, v11
	v_fma_f32 v8, v156, v212, v8
	v_fma_f32 v9, v156, v216, v9
	v_fma_f32 v6, v156, v220, v6
	v_fma_f32 v7, v156, v224, v7
	v_fma_f32 v4, v156, v228, v4
	v_fma_f32 v5, v156, v232, v5
	v_fma_f32 v10, v157, v205, v10
	v_fma_f32 v11, v157, v209, v11
	v_fma_f32 v8, v157, v213, v8
	v_fma_f32 v9, v157, v217, v9
	v_fma_f32 v6, v157, v221, v6
	v_fma_f32 v7, v157, v225, v7
	v_fma_f32 v4, v157, v229, v4
	v_fma_f32 v5, v157, v233, v5
	v_fma_f32 v10, v158, v206, v10
	v_fma_f32 v11, v158, v210, v11
	v_fma_f32 v8, v158, v214, v8
	v_fma_f32 v9, v158, v218, v9
	v_fma_f32 v6, v158, v222, v6
	v_fma_f32 v7, v158, v226, v7
	v_fma_f32 v4, v158, v230, v4
	v_fma_f32 v5, v158, v234, v5
	v_fma_f32 v10, v159, v207, v10
	v_fma_f32 v11, v159, v211, v11
	v_fma_f32 v8, v159, v215, v8
	v_fma_f32 v9, v159, v219, v9
	v_fma_f32 v6, v159, v223, v6
	v_fma_f32 v7, v159, v227, v7
	v_fma_f32 v4, v159, v231, v4
	v_fma_f32 v5, v159, v235, v5
	ds_read_b128 v[204:207], v202 offset:400
	ds_read_b128 v[208:211], v202 offset:4496
	ds_read_b128 v[212:215], v202 offset:8592
	ds_read_b128 v[216:219], v202 offset:12688
	ds_read_b128 v[220:223], v202 offset:16784
	ds_read_b128 v[224:227], v202 offset:20880
	ds_read_b128 v[228:231], v202 offset:24976
	ds_read_b128 v[232:235], v202 offset:29072
	s_waitcnt vmcnt(28) lgkmcnt(8)
	v_fma_f32 v10, v160, v14, v10
	v_fma_f32 v11, v160, v18, v11
	v_fma_f32 v8, v160, v22, v8
	v_fma_f32 v9, v160, v26, v9
	v_fma_f32 v6, v160, v30, v6
	v_fma_f32 v7, v160, v34, v7
	v_fma_f32 v4, v160, v38, v4
	v_fma_f32 v5, v160, v42, v5
	v_fma_f32 v10, v161, v15, v10
	v_fma_f32 v11, v161, v19, v11
	v_fma_f32 v8, v161, v23, v8
	v_fma_f32 v9, v161, v27, v9
	v_fma_f32 v6, v161, v31, v6
	v_fma_f32 v7, v161, v35, v7
	v_fma_f32 v4, v161, v39, v4
	v_fma_f32 v5, v161, v43, v5
	v_fma_f32 v10, v162, v16, v10
	v_fma_f32 v11, v162, v20, v11
	v_fma_f32 v8, v162, v24, v8
	v_fma_f32 v9, v162, v28, v9
	v_fma_f32 v6, v162, v32, v6
	v_fma_f32 v7, v162, v36, v7
	v_fma_f32 v4, v162, v40, v4
	v_fma_f32 v5, v162, v44, v5
	v_fma_f32 v10, v163, v17, v10
	v_fma_f32 v11, v163, v21, v11
	v_fma_f32 v8, v163, v25, v8
	v_fma_f32 v9, v163, v29, v9
	v_fma_f32 v6, v163, v33, v6
	v_fma_f32 v7, v163, v37, v7
	v_fma_f32 v4, v163, v41, v4
	v_fma_f32 v5, v163, v45, v5
	ds_read_b128 v[14:17], v202 offset:416
	ds_read_b128 v[18:21], v202 offset:4512
	ds_read_b128 v[22:25], v202 offset:8608
	ds_read_b128 v[26:29], v202 offset:12704
	ds_read_b128 v[30:33], v202 offset:16800
	ds_read_b128 v[34:37], v202 offset:20896
	ds_read_b128 v[38:41], v202 offset:24992
	ds_read_b128 v[42:45], v202 offset:29088
	s_waitcnt vmcnt(24) lgkmcnt(8)
	v_fma_f32 v10, v164, v204, v10
	v_fma_f32 v11, v164, v208, v11
	v_fma_f32 v8, v164, v212, v8
	v_fma_f32 v9, v164, v216, v9
	v_fma_f32 v6, v164, v220, v6
	v_fma_f32 v7, v164, v224, v7
	v_fma_f32 v4, v164, v228, v4
	v_fma_f32 v5, v164, v232, v5
	v_fma_f32 v10, v165, v205, v10
	v_fma_f32 v11, v165, v209, v11
	v_fma_f32 v8, v165, v213, v8
	v_fma_f32 v9, v165, v217, v9
	v_fma_f32 v6, v165, v221, v6
	v_fma_f32 v7, v165, v225, v7
	v_fma_f32 v4, v165, v229, v4
	v_fma_f32 v5, v165, v233, v5
	v_fma_f32 v10, v166, v206, v10
	v_fma_f32 v11, v166, v210, v11
	v_fma_f32 v8, v166, v214, v8
	v_fma_f32 v9, v166, v218, v9
	v_fma_f32 v6, v166, v222, v6
	v_fma_f32 v7, v166, v226, v7
	v_fma_f32 v4, v166, v230, v4
	v_fma_f32 v5, v166, v234, v5
	v_fma_f32 v10, v167, v207, v10
	v_fma_f32 v11, v167, v211, v11
	v_fma_f32 v8, v167, v215, v8
	v_fma_f32 v9, v167, v219, v9
	v_fma_f32 v6, v167, v223, v6
	v_fma_f32 v7, v167, v227, v7
	v_fma_f32 v4, v167, v231, v4
	v_fma_f32 v5, v167, v235, v5
	ds_read_b128 v[204:207], v202 offset:432
	ds_read_b128 v[208:211], v202 offset:4528
	ds_read_b128 v[212:215], v202 offset:8624
	ds_read_b128 v[216:219], v202 offset:12720
	ds_read_b128 v[220:223], v202 offset:16816
	ds_read_b128 v[224:227], v202 offset:20912
	ds_read_b128 v[228:231], v202 offset:25008
	ds_read_b128 v[232:235], v202 offset:29104
	s_waitcnt vmcnt(20) lgkmcnt(8)
	v_fma_f32 v10, v168, v14, v10
	v_fma_f32 v11, v168, v18, v11
	v_fma_f32 v8, v168, v22, v8
	v_fma_f32 v9, v168, v26, v9
	v_fma_f32 v6, v168, v30, v6
	v_fma_f32 v7, v168, v34, v7
	v_fma_f32 v4, v168, v38, v4
	v_fma_f32 v5, v168, v42, v5
	v_fma_f32 v10, v169, v15, v10
	v_fma_f32 v11, v169, v19, v11
	v_fma_f32 v8, v169, v23, v8
	v_fma_f32 v9, v169, v27, v9
	v_fma_f32 v6, v169, v31, v6
	v_fma_f32 v7, v169, v35, v7
	v_fma_f32 v4, v169, v39, v4
	v_fma_f32 v5, v169, v43, v5
	v_fma_f32 v10, v170, v16, v10
	v_fma_f32 v11, v170, v20, v11
	v_fma_f32 v8, v170, v24, v8
	v_fma_f32 v9, v170, v28, v9
	v_fma_f32 v6, v170, v32, v6
	v_fma_f32 v7, v170, v36, v7
	v_fma_f32 v4, v170, v40, v4
	v_fma_f32 v5, v170, v44, v5
	v_fma_f32 v10, v171, v17, v10
	v_fma_f32 v11, v171, v21, v11
	v_fma_f32 v8, v171, v25, v8
	v_fma_f32 v9, v171, v29, v9
	v_fma_f32 v6, v171, v33, v6
	v_fma_f32 v7, v171, v37, v7
	v_fma_f32 v4, v171, v41, v4
	v_fma_f32 v5, v171, v45, v5
	ds_read_b128 v[14:17], v202 offset:448
	ds_read_b128 v[18:21], v202 offset:4544
	ds_read_b128 v[22:25], v202 offset:8640
	ds_read_b128 v[26:29], v202 offset:12736
	ds_read_b128 v[30:33], v202 offset:16832
	ds_read_b128 v[34:37], v202 offset:20928
	ds_read_b128 v[38:41], v202 offset:25024
	ds_read_b128 v[42:45], v202 offset:29120
	s_waitcnt vmcnt(16) lgkmcnt(8)
	v_fma_f32 v10, v172, v204, v10
	v_fma_f32 v11, v172, v208, v11
	v_fma_f32 v8, v172, v212, v8
	v_fma_f32 v9, v172, v216, v9
	v_fma_f32 v6, v172, v220, v6
	v_fma_f32 v7, v172, v224, v7
	v_fma_f32 v4, v172, v228, v4
	v_fma_f32 v5, v172, v232, v5
	v_fma_f32 v10, v173, v205, v10
	v_fma_f32 v11, v173, v209, v11
	v_fma_f32 v8, v173, v213, v8
	v_fma_f32 v9, v173, v217, v9
	v_fma_f32 v6, v173, v221, v6
	v_fma_f32 v7, v173, v225, v7
	v_fma_f32 v4, v173, v229, v4
	v_fma_f32 v5, v173, v233, v5
	v_fma_f32 v10, v174, v206, v10
	v_fma_f32 v11, v174, v210, v11
	v_fma_f32 v8, v174, v214, v8
	v_fma_f32 v9, v174, v218, v9
	v_fma_f32 v6, v174, v222, v6
	v_fma_f32 v7, v174, v226, v7
	v_fma_f32 v4, v174, v230, v4
	v_fma_f32 v5, v174, v234, v5
	v_fma_f32 v10, v175, v207, v10
	v_fma_f32 v11, v175, v211, v11
	v_fma_f32 v8, v175, v215, v8
	v_fma_f32 v9, v175, v219, v9
	v_fma_f32 v6, v175, v223, v6
	v_fma_f32 v7, v175, v227, v7
	v_fma_f32 v4, v175, v231, v4
	v_fma_f32 v5, v175, v235, v5
	ds_read_b128 v[204:207], v202 offset:464
	ds_read_b128 v[208:211], v202 offset:4560
	ds_read_b128 v[212:215], v202 offset:8656
	ds_read_b128 v[216:219], v202 offset:12752
	ds_read_b128 v[220:223], v202 offset:16848
	ds_read_b128 v[224:227], v202 offset:20944
	ds_read_b128 v[228:231], v202 offset:25040
	ds_read_b128 v[232:235], v202 offset:29136
	s_waitcnt vmcnt(12) lgkmcnt(8)
	v_fma_f32 v10, v176, v14, v10
	v_fma_f32 v11, v176, v18, v11
	v_fma_f32 v8, v176, v22, v8
	v_fma_f32 v9, v176, v26, v9
	v_fma_f32 v6, v176, v30, v6
	v_fma_f32 v7, v176, v34, v7
	v_fma_f32 v4, v176, v38, v4
	v_fma_f32 v5, v176, v42, v5
	v_fma_f32 v10, v177, v15, v10
	v_fma_f32 v11, v177, v19, v11
	v_fma_f32 v8, v177, v23, v8
	v_fma_f32 v9, v177, v27, v9
	v_fma_f32 v6, v177, v31, v6
	v_fma_f32 v7, v177, v35, v7
	v_fma_f32 v4, v177, v39, v4
	v_fma_f32 v5, v177, v43, v5
	v_fma_f32 v10, v178, v16, v10
	v_fma_f32 v11, v178, v20, v11
	v_fma_f32 v8, v178, v24, v8
	v_fma_f32 v9, v178, v28, v9
	v_fma_f32 v6, v178, v32, v6
	v_fma_f32 v7, v178, v36, v7
	v_fma_f32 v4, v178, v40, v4
	v_fma_f32 v5, v178, v44, v5
	v_fma_f32 v10, v180, v17, v10
	v_fma_f32 v11, v180, v21, v11
	v_fma_f32 v8, v180, v25, v8
	v_fma_f32 v9, v180, v29, v9
	v_fma_f32 v6, v180, v33, v6
	v_fma_f32 v7, v180, v37, v7
	v_fma_f32 v4, v180, v41, v4
	v_fma_f32 v5, v180, v45, v5
	ds_read_b128 v[14:17], v202 offset:480
	ds_read_b128 v[18:21], v202 offset:4576
	ds_read_b128 v[22:25], v202 offset:8672
	ds_read_b128 v[26:29], v202 offset:12768
	ds_read_b128 v[30:33], v202 offset:16864
	ds_read_b128 v[34:37], v202 offset:20960
	ds_read_b128 v[38:41], v202 offset:25056
	ds_read_b128 v[42:45], v202 offset:29152
	s_waitcnt vmcnt(8) lgkmcnt(8)
	v_fma_f32 v10, v181, v204, v10
	v_fma_f32 v11, v181, v208, v11
	v_fma_f32 v8, v181, v212, v8
	v_fma_f32 v9, v181, v216, v9
	v_fma_f32 v6, v181, v220, v6
	v_fma_f32 v7, v181, v224, v7
	v_fma_f32 v4, v181, v228, v4
	v_fma_f32 v5, v181, v232, v5
	v_fma_f32 v10, v182, v205, v10
	v_fma_f32 v11, v182, v209, v11
	v_fma_f32 v8, v182, v213, v8
	v_fma_f32 v9, v182, v217, v9
	v_fma_f32 v6, v182, v221, v6
	v_fma_f32 v7, v182, v225, v7
	v_fma_f32 v4, v182, v229, v4
	v_fma_f32 v5, v182, v233, v5
	v_fma_f32 v10, v183, v206, v10
	v_fma_f32 v11, v183, v210, v11
	v_fma_f32 v8, v183, v214, v8
	v_fma_f32 v9, v183, v218, v9
	v_fma_f32 v6, v183, v222, v6
	v_fma_f32 v7, v183, v226, v7
	v_fma_f32 v4, v183, v230, v4
	v_fma_f32 v5, v183, v234, v5
	v_fma_f32 v10, v184, v207, v10
	v_fma_f32 v11, v184, v211, v11
	v_fma_f32 v8, v184, v215, v8
	v_fma_f32 v9, v184, v219, v9
	v_fma_f32 v6, v184, v223, v6
	v_fma_f32 v7, v184, v227, v7
	v_fma_f32 v4, v184, v231, v4
	v_fma_f32 v5, v184, v235, v5
	ds_read_b128 v[204:207], v202 offset:496
	ds_read_b128 v[208:211], v202 offset:4592
	ds_read_b128 v[212:215], v202 offset:8688
	ds_read_b128 v[216:219], v202 offset:12784
	ds_read_b128 v[220:223], v202 offset:16880
	ds_read_b128 v[224:227], v202 offset:20976
	ds_read_b128 v[228:231], v202 offset:25072
	ds_read_b128 v[232:235], v202 offset:29168
	s_waitcnt vmcnt(4) lgkmcnt(8)
	v_fma_f32 v10, v185, v14, v10
	v_fma_f32 v11, v185, v18, v11
	v_fma_f32 v8, v185, v22, v8
	v_fma_f32 v9, v185, v26, v9
	v_fma_f32 v6, v185, v30, v6
	v_fma_f32 v7, v185, v34, v7
	v_fma_f32 v4, v185, v38, v4
	v_fma_f32 v5, v185, v42, v5
	v_fma_f32 v10, v186, v15, v10
	v_fma_f32 v11, v186, v19, v11
	v_fma_f32 v8, v186, v23, v8
	v_fma_f32 v9, v186, v27, v9
	v_fma_f32 v6, v186, v31, v6
	v_fma_f32 v7, v186, v35, v7
	v_fma_f32 v4, v186, v39, v4
	v_fma_f32 v5, v186, v43, v5
	v_fma_f32 v10, v187, v16, v10
	v_fma_f32 v11, v187, v20, v11
	v_fma_f32 v8, v187, v24, v8
	v_fma_f32 v9, v187, v28, v9
	v_fma_f32 v6, v187, v32, v6
	v_fma_f32 v7, v187, v36, v7
	v_fma_f32 v4, v187, v40, v4
	v_fma_f32 v5, v187, v44, v5
	v_fma_f32 v10, v188, v17, v10
	v_fma_f32 v11, v188, v21, v11
	v_fma_f32 v8, v188, v25, v8
	v_fma_f32 v9, v188, v29, v9
	v_fma_f32 v6, v188, v33, v6
	v_fma_f32 v7, v188, v37, v7
	v_fma_f32 v4, v188, v41, v4
	v_fma_f32 v5, v188, v45, v5
	s_waitcnt vmcnt(0) lgkmcnt(0)
	v_fma_f32 v10, v189, v204, v10
	v_fma_f32 v11, v189, v208, v11
	v_fma_f32 v8, v189, v212, v8
	v_fma_f32 v9, v189, v216, v9
	v_fma_f32 v6, v189, v220, v6
	v_fma_f32 v7, v189, v224, v7
	v_fma_f32 v4, v189, v228, v4
	v_fma_f32 v5, v189, v232, v5
	v_fma_f32 v10, v190, v205, v10
	v_fma_f32 v11, v190, v209, v11
	v_fma_f32 v8, v190, v213, v8
	v_fma_f32 v9, v190, v217, v9
	v_fma_f32 v6, v190, v221, v6
	v_fma_f32 v7, v190, v225, v7
	v_fma_f32 v4, v190, v229, v4
	v_fma_f32 v5, v190, v233, v5
	v_fma_f32 v10, v191, v206, v10
	v_fma_f32 v11, v191, v210, v11
	v_fma_f32 v8, v191, v214, v8
	v_fma_f32 v9, v191, v218, v9
	v_fma_f32 v6, v191, v222, v6
	v_fma_f32 v7, v191, v226, v7
	v_fma_f32 v4, v191, v230, v4
	v_fma_f32 v5, v191, v234, v5
	v_fma_f32 v10, v192, v207, v10
	v_fma_f32 v11, v192, v211, v11
	v_fma_f32 v8, v192, v215, v8
	v_fma_f32 v9, v192, v219, v9
	v_fma_f32 v6, v192, v223, v6
	v_fma_f32 v7, v192, v227, v7
	v_fma_f32 v4, v192, v231, v4
	v_fma_f32 v5, v192, v235, v5
.Lada_join:
	s_cmp_eq_u32 s9, 0
	v_mov_b32_e32 v12, 0
	s_cbranch_scc0 .LBB0_19
	s_mul_i32 s0, s8, 0x2400
	v_add_u32_e32 v12, s0, v2
	v_readlane_b32 s36, v249, 0
	v_ashrrev_i32_e32 v13, 31, v12
	v_readlane_b32 s42, v249, 6
	v_readlane_b32 s43, v249, 7
	v_readlane_b32 s37, v249, 1
	v_readlane_b32 s38, v249, 2
	v_lshl_add_u64 v[12:13], v[12:13], 2, s[42:43]
	global_load_dword v12, v[12:13], off
	v_readlane_b32 s39, v249, 3
	v_readlane_b32 s40, v249, 4
	v_readlane_b32 s41, v249, 5
	s_branch .LBB0_19
